# adds hand-written pipelined short-conv loop in P2 (3 items in flight, scalar row bases, weights loaded once); compiler loop only redoes sequence-start rows
# baseline (speedup 1.0000x reference)
.LBB0_403:
	v_readlane_b32 s84, v248, 32
	v_readlane_b32 s82, v248, 37
	s_cmp_gt_i32 s84, 63
	v_readlane_b32 s66, v248, 30
	v_readlane_b32 s83, v248, 38
	v_readlane_b32 s67, v248, 31
	s_cbranch_scc0 .LBB0_440
	s_lshl_b32 s0, s84, 3
	v_readlane_b32 s1, v248, 0
	s_add_i32 s0, s0, s1
	s_lshl_b32 s0, s0, 6
	s_addk_i32 s0, 0x8000
	s_lshl_b32 s19, s95, 9
	v_or_b32_e32 v26, s0, v206
	s_mov_b32 s0, 0x240000
	s_mov_b64 s[2:3], s[96:97]
	s_mov_b64 s[6:7], s[96:97]
	s_add_i32 s18, s19, 0xffff8000
	v_cmp_gt_i32_e32 vcc, s0, v26
	s_and_saveexec_b64 s[0:1], vcc
	s_cbranch_execz .LBB0_427
	v_readfirstlane_b32 s4, v26
	s_load_dwordx2 s[10:11], s[2:3], 0x90
	v_and_b32_e32 v96, 0xff, v26
	v_lshlrev_b32_e32 v97, 5, v96
	v_lshlrev_b32_e32 v96, 4, v96
	v_add_u32_e32 v98, 0x2000, v97
	v_add_u32_e32 v99, 0x4000, v97
	s_lshr_b32 s4, s4, 8
	s_lshl_b32 s4, s4, 12
	v_readlane_b32 s8, v248, 45
	v_readlane_b32 s9, v248, 46
	v_readlane_b32 s12, v248, 49
	v_readlane_b32 s13, v248, 50
	s_nop 3
	s_add_u32 s20, s8, s4
	s_addc_u32 s21, s9, 0
	s_add_u32 s24, s12, s4
	s_addc_u32 s25, s13, 0
	s_add_u32 s26, s70, s4
	s_addc_u32 s27, s71, 0
	s_sub_u32 s22, s20, 0x2000
	s_subb_u32 s23, s21, 0
	s_waitcnt lgkmcnt(0)
	global_load_dwordx4 v[72:75], v97, s[10:11]
	global_load_dwordx4 v[76:79], v97, s[10:11] offset:16
	global_load_dwordx4 v[80:83], v98, s[10:11]
	global_load_dwordx4 v[84:87], v98, s[10:11] offset:16
	global_load_dwordx4 v[88:91], v99, s[10:11]
	global_load_dwordx4 v[92:95], v99, s[10:11] offset:16
	global_load_dwordx4 v[100:103], v96, s[20:21]
	global_load_dwordx4 v[104:107], v96, s[20:21] offset:-4096
	global_load_dwordx4 v[108:111], v96, s[22:23]
	global_load_dwordx4 v[112:115], v96, s[24:25]
	s_add_u32 s20, s20, 0x180000
	s_addc_u32 s21, s21, 0
	s_add_u32 s22, s22, 0x180000
	s_addc_u32 s23, s23, 0
	s_add_u32 s24, s24, 0x180000
	s_addc_u32 s25, s25, 0
	global_load_dwordx4 v[116:119], v96, s[20:21]
	global_load_dwordx4 v[120:123], v96, s[20:21] offset:-4096
	global_load_dwordx4 v[124:127], v96, s[22:23]
	global_load_dwordx4 v[128:131], v96, s[24:25]
	s_add_u32 s20, s20, 0x180000
	s_addc_u32 s21, s21, 0
	s_add_u32 s22, s22, 0x180000
	s_addc_u32 s23, s23, 0
	s_add_u32 s24, s24, 0x180000
	s_addc_u32 s25, s25, 0
	s_mov_b32 s28, 8
.Lconv_trip:
	global_load_dwordx4 v[132:135], v96, s[20:21]
	global_load_dwordx4 v[136:139], v96, s[20:21] offset:-4096
	global_load_dwordx4 v[140:143], v96, s[22:23]
	global_load_dwordx4 v[144:147], v96, s[24:25]
	s_add_u32 s20, s20, 0x180000
	s_addc_u32 s21, s21, 0
	s_add_u32 s22, s22, 0x180000
	s_addc_u32 s23, s23, 0
	s_add_u32 s24, s24, 0x180000
	s_addc_u32 s25, s25, 0
	s_waitcnt vmcnt(8)
	v_lshlrev_b32_e32 v148, 16, v108
	v_lshlrev_b32_e32 v149, 16, v104
	v_lshlrev_b32_e32 v150, 16, v100
	v_lshlrev_b32_e32 v151, 16, v112
	v_and_b32_e32 v152, 0xffff0000, v108
	v_and_b32_e32 v153, 0xffff0000, v104
	v_and_b32_e32 v154, 0xffff0000, v100
	v_and_b32_e32 v155, 0xffff0000, v112
	v_mul_f32_e32 v148, v72, v148
	v_mul_f32_e32 v152, v73, v152
	v_fmac_f32_e32 v148, v80, v149
	v_fmac_f32_e32 v152, v81, v153
	v_fmac_f32_e32 v148, v88, v150
	v_fmac_f32_e32 v152, v89, v154
	v_mul_f32_e32 v148, v151, v148
	v_mul_f32_e32 v152, v155, v152
	v_cvt_pk_bf16_f32 v158, v148, v152
	v_lshlrev_b32_e32 v148, 16, v109
	v_lshlrev_b32_e32 v149, 16, v105
	v_lshlrev_b32_e32 v150, 16, v101
	v_lshlrev_b32_e32 v151, 16, v113
	v_and_b32_e32 v152, 0xffff0000, v109
	v_and_b32_e32 v153, 0xffff0000, v105
	v_and_b32_e32 v154, 0xffff0000, v101
	v_and_b32_e32 v155, 0xffff0000, v113
	v_mul_f32_e32 v148, v74, v148
	v_mul_f32_e32 v152, v75, v152
	v_fmac_f32_e32 v148, v82, v149
	v_fmac_f32_e32 v152, v83, v153
	v_fmac_f32_e32 v148, v90, v150
	v_fmac_f32_e32 v152, v91, v154
	v_mul_f32_e32 v148, v151, v148
	v_mul_f32_e32 v152, v155, v152
	v_cvt_pk_bf16_f32 v159, v148, v152
	v_lshlrev_b32_e32 v148, 16, v110
	v_lshlrev_b32_e32 v149, 16, v106
	v_lshlrev_b32_e32 v150, 16, v102
	v_lshlrev_b32_e32 v151, 16, v114
	v_and_b32_e32 v152, 0xffff0000, v110
	v_and_b32_e32 v153, 0xffff0000, v106
	v_and_b32_e32 v154, 0xffff0000, v102
	v_and_b32_e32 v155, 0xffff0000, v114
	v_mul_f32_e32 v148, v76, v148
	v_mul_f32_e32 v152, v77, v152
	v_fmac_f32_e32 v148, v84, v149
	v_fmac_f32_e32 v152, v85, v153
	v_fmac_f32_e32 v148, v92, v150
	v_fmac_f32_e32 v152, v93, v154
	v_mul_f32_e32 v148, v151, v148
	v_mul_f32_e32 v152, v155, v152
	v_cvt_pk_bf16_f32 v160, v148, v152
	v_lshlrev_b32_e32 v148, 16, v111
	v_lshlrev_b32_e32 v149, 16, v107
	v_lshlrev_b32_e32 v150, 16, v103
	v_lshlrev_b32_e32 v151, 16, v115
	v_and_b32_e32 v152, 0xffff0000, v111
	v_and_b32_e32 v153, 0xffff0000, v107
	v_and_b32_e32 v154, 0xffff0000, v103
	v_and_b32_e32 v155, 0xffff0000, v115
	v_mul_f32_e32 v148, v78, v148
	v_mul_f32_e32 v152, v79, v152
	v_fmac_f32_e32 v148, v86, v149
	v_fmac_f32_e32 v152, v87, v153
	v_fmac_f32_e32 v148, v94, v150
	v_fmac_f32_e32 v152, v95, v154
	v_mul_f32_e32 v148, v151, v148
	v_mul_f32_e32 v152, v155, v152
	v_cvt_pk_bf16_f32 v161, v148, v152
	global_store_dwordx4 v96, v[158:161], s[26:27]
	s_add_u32 s26, s26, 0x180000
	s_addc_u32 s27, s27, 0
	global_load_dwordx4 v[100:103], v96, s[20:21]
	global_load_dwordx4 v[104:107], v96, s[20:21] offset:-4096
	global_load_dwordx4 v[108:111], v96, s[22:23]
	global_load_dwordx4 v[112:115], v96, s[24:25]
	s_add_u32 s20, s20, 0x180000
	s_addc_u32 s21, s21, 0
	s_add_u32 s22, s22, 0x180000
	s_addc_u32 s23, s23, 0
	s_add_u32 s24, s24, 0x180000
	s_addc_u32 s25, s25, 0
	s_waitcnt vmcnt(8)
	v_lshlrev_b32_e32 v148, 16, v124
	v_lshlrev_b32_e32 v149, 16, v120
	v_lshlrev_b32_e32 v150, 16, v116
	v_lshlrev_b32_e32 v151, 16, v128
	v_and_b32_e32 v152, 0xffff0000, v124
	v_and_b32_e32 v153, 0xffff0000, v120
	v_and_b32_e32 v154, 0xffff0000, v116
	v_and_b32_e32 v155, 0xffff0000, v128
	v_mul_f32_e32 v148, v72, v148
	v_mul_f32_e32 v152, v73, v152
	v_fmac_f32_e32 v148, v80, v149
	v_fmac_f32_e32 v152, v81, v153
	v_fmac_f32_e32 v148, v88, v150
	v_fmac_f32_e32 v152, v89, v154
	v_mul_f32_e32 v148, v151, v148
	v_mul_f32_e32 v152, v155, v152
	v_cvt_pk_bf16_f32 v158, v148, v152
	v_lshlrev_b32_e32 v148, 16, v125
	v_lshlrev_b32_e32 v149, 16, v121
	v_lshlrev_b32_e32 v150, 16, v117
	v_lshlrev_b32_e32 v151, 16, v129
	v_and_b32_e32 v152, 0xffff0000, v125
	v_and_b32_e32 v153, 0xffff0000, v121
	v_and_b32_e32 v154, 0xffff0000, v117
	v_and_b32_e32 v155, 0xffff0000, v129
	v_mul_f32_e32 v148, v74, v148
	v_mul_f32_e32 v152, v75, v152
	v_fmac_f32_e32 v148, v82, v149
	v_fmac_f32_e32 v152, v83, v153
	v_fmac_f32_e32 v148, v90, v150
	v_fmac_f32_e32 v152, v91, v154
	v_mul_f32_e32 v148, v151, v148
	v_mul_f32_e32 v152, v155, v152
	v_cvt_pk_bf16_f32 v159, v148, v152
	v_lshlrev_b32_e32 v148, 16, v126
	v_lshlrev_b32_e32 v149, 16, v122
	v_lshlrev_b32_e32 v150, 16, v118
	v_lshlrev_b32_e32 v151, 16, v130
	v_and_b32_e32 v152, 0xffff0000, v126
	v_and_b32_e32 v153, 0xffff0000, v122
	v_and_b32_e32 v154, 0xffff0000, v118
	v_and_b32_e32 v155, 0xffff0000, v130
	v_mul_f32_e32 v148, v76, v148
	v_mul_f32_e32 v152, v77, v152
	v_fmac_f32_e32 v148, v84, v149
	v_fmac_f32_e32 v152, v85, v153
	v_fmac_f32_e32 v148, v92, v150
	v_fmac_f32_e32 v152, v93, v154
	v_mul_f32_e32 v148, v151, v148
	v_mul_f32_e32 v152, v155, v152
	v_cvt_pk_bf16_f32 v160, v148, v152
	v_lshlrev_b32_e32 v148, 16, v127
	v_lshlrev_b32_e32 v149, 16, v123
	v_lshlrev_b32_e32 v150, 16, v119
	v_lshlrev_b32_e32 v151, 16, v131
	v_and_b32_e32 v152, 0xffff0000, v127
	v_and_b32_e32 v153, 0xffff0000, v123
	v_and_b32_e32 v154, 0xffff0000, v119
	v_and_b32_e32 v155, 0xffff0000, v131
	v_mul_f32_e32 v148, v78, v148
	v_mul_f32_e32 v152, v79, v152
	v_fmac_f32_e32 v148, v86, v149
	v_fmac_f32_e32 v152, v87, v153
	v_fmac_f32_e32 v148, v94, v150
	v_fmac_f32_e32 v152, v95, v154
	v_mul_f32_e32 v148, v151, v148
	v_mul_f32_e32 v152, v155, v152
	v_cvt_pk_bf16_f32 v161, v148, v152
	global_store_dwordx4 v96, v[158:161], s[26:27]
	s_add_u32 s26, s26, 0x180000
	s_addc_u32 s27, s27, 0
	global_load_dwordx4 v[116:119], v96, s[20:21]
	global_load_dwordx4 v[120:123], v96, s[20:21] offset:-4096
	global_load_dwordx4 v[124:127], v96, s[22:23]
	global_load_dwordx4 v[128:131], v96, s[24:25]
	s_add_u32 s20, s20, 0x180000
	s_addc_u32 s21, s21, 0
	s_add_u32 s22, s22, 0x180000
	s_addc_u32 s23, s23, 0
	s_add_u32 s24, s24, 0x180000
	s_addc_u32 s25, s25, 0
	s_waitcnt vmcnt(8)
	v_lshlrev_b32_e32 v148, 16, v140
	v_lshlrev_b32_e32 v149, 16, v136
	v_lshlrev_b32_e32 v150, 16, v132
	v_lshlrev_b32_e32 v151, 16, v144
	v_and_b32_e32 v152, 0xffff0000, v140
	v_and_b32_e32 v153, 0xffff0000, v136
	v_and_b32_e32 v154, 0xffff0000, v132
	v_and_b32_e32 v155, 0xffff0000, v144
	v_mul_f32_e32 v148, v72, v148
	v_mul_f32_e32 v152, v73, v152
	v_fmac_f32_e32 v148, v80, v149
	v_fmac_f32_e32 v152, v81, v153
	v_fmac_f32_e32 v148, v88, v150
	v_fmac_f32_e32 v152, v89, v154
	v_mul_f32_e32 v148, v151, v148
	v_mul_f32_e32 v152, v155, v152
	v_cvt_pk_bf16_f32 v158, v148, v152
	v_lshlrev_b32_e32 v148, 16, v141
	v_lshlrev_b32_e32 v149, 16, v137
	v_lshlrev_b32_e32 v150, 16, v133
	v_lshlrev_b32_e32 v151, 16, v145
	v_and_b32_e32 v152, 0xffff0000, v141
	v_and_b32_e32 v153, 0xffff0000, v137
	v_and_b32_e32 v154, 0xffff0000, v133
	v_and_b32_e32 v155, 0xffff0000, v145
	v_mul_f32_e32 v148, v74, v148
	v_mul_f32_e32 v152, v75, v152
	v_fmac_f32_e32 v148, v82, v149
	v_fmac_f32_e32 v152, v83, v153
	v_fmac_f32_e32 v148, v90, v150
	v_fmac_f32_e32 v152, v91, v154
	v_mul_f32_e32 v148, v151, v148
	v_mul_f32_e32 v152, v155, v152
	v_cvt_pk_bf16_f32 v159, v148, v152
	v_lshlrev_b32_e32 v148, 16, v142
	v_lshlrev_b32_e32 v149, 16, v138
	v_lshlrev_b32_e32 v150, 16, v134
	v_lshlrev_b32_e32 v151, 16, v146
	v_and_b32_e32 v152, 0xffff0000, v142
	v_and_b32_e32 v153, 0xffff0000, v138
	v_and_b32_e32 v154, 0xffff0000, v134
	v_and_b32_e32 v155, 0xffff0000, v146
	v_mul_f32_e32 v148, v76, v148
	v_mul_f32_e32 v152, v77, v152
	v_fmac_f32_e32 v148, v84, v149
	v_fmac_f32_e32 v152, v85, v153
	v_fmac_f32_e32 v148, v92, v150
	v_fmac_f32_e32 v152, v93, v154
	v_mul_f32_e32 v148, v151, v148
	v_mul_f32_e32 v152, v155, v152
	v_cvt_pk_bf16_f32 v160, v148, v152
	v_lshlrev_b32_e32 v148, 16, v143
	v_lshlrev_b32_e32 v149, 16, v139
	v_lshlrev_b32_e32 v150, 16, v135
	v_lshlrev_b32_e32 v151, 16, v147
	v_and_b32_e32 v152, 0xffff0000, v143
	v_and_b32_e32 v153, 0xffff0000, v139
	v_and_b32_e32 v154, 0xffff0000, v135
	v_and_b32_e32 v155, 0xffff0000, v147
	v_mul_f32_e32 v148, v78, v148
	v_mul_f32_e32 v152, v79, v152
	v_fmac_f32_e32 v148, v86, v149
	v_fmac_f32_e32 v152, v87, v153
	v_fmac_f32_e32 v148, v94, v150
	v_fmac_f32_e32 v152, v95, v154
	v_mul_f32_e32 v148, v151, v148
	v_mul_f32_e32 v152, v155, v152
	v_cvt_pk_bf16_f32 v161, v148, v152
	global_store_dwordx4 v96, v[158:161], s[26:27]
	s_add_u32 s26, s26, 0x180000
	s_addc_u32 s27, s27, 0
	s_sub_u32 s28, s28, 1
	s_cmp_lg_u32 s28, 0
	s_cbranch_scc1 .Lconv_trip
	s_load_dwordx2 s[4:5], s[2:3], 0x20
	s_nop 0
	s_load_dwordx2 s[6:7], s[6:7], 0x90
	s_lshl_b32 s20, s95, 12
	v_lshlrev_b32_e32 v1, 3, v26
	s_add_i32 s20, s20, 0xfffc0000
	s_mov_b64 s[8:9], 0
	v_mov_b32_e32 v29, 0
	s_movk_i32 s21, 0x1fff
	s_movk_i32 s22, 0x1800
	s_mov_b32 s23, 0xffff0000
	s_movk_i32 s24, 0xf00
	s_movk_i32 s25, 0x2000
	s_mov_b64 s[10:11], 0x2000
	s_mov_b64 s[12:13], 0x4000
	s_movk_i32 s26, 0x4000
	s_movk_i32 s27, 0x7fff
	s_mov_b32 s28, 0x23ffff
	v_mov_b32_e32 v27, 0x15000
	v_mov_b32_e32 v38, 0xffffe800
	v_mov_b32_e32 v39, 0x16800
	v_mov_b32_e32 v40, 0x2000
	v_mov_b32_e32 v41, v26
	s_branch .LBB0_407

.LBB0_407:
	v_readfirstlane_b32 s16, v41
	s_lshr_b32 s16, s16, 8
	s_cmp_lt_u32 s16, 0x2000
	s_cselect_b32 s17, 0x7ff, 7
	s_and_b32 s16, s16, s17
	s_cmp_lt_u32 s16, 2
	s_cbranch_scc1 .Lconv_special
	v_add_u32_e32 v41, s18, v41
	v_add_u32_e32 v1, s20, v1
	v_cmp_lt_i32_e32 vcc, s28, v41
	s_or_b64 s[8:9], vcc, s[8:9]
	s_andn2_b64 exec, exec, s[8:9]
	s_cbranch_execz .LBB0_427
	s_branch .LBB0_407
